# prep phase de-serialisation: the 35 row-invariant parameter loads of the rwkv part are issued 8 sites ahead into spare registers with counted waits (was load / vmcnt(0) / store per element)
# speedup vs baseline: 1.1118x; 1.0190x over previous
.LBB0_304:
	s_or_b64 exec, exec, s[2:3]
	global_load_dword v236, v[38:39], off
	global_load_dword v237, v[30:31], off offset:1024
	global_load_dword v238, v[30:31], off offset:1280
	global_load_dword v239, v[30:31], off offset:1536
	global_load_dword v240, v[40:41], off
	global_load_dword v241, v[30:31], off offset:2048
	global_load_dword v242, v[78:79], off
	global_load_dword v243, v[30:31], off offset:2304
	v_lshlrev_b64 v[136:137], 9, v[106:107]
	v_add_f32_e32 v111, v111, v169
	v_fma_f32 v111, v111, 0.5, -v109
	v_readlane_b32 s4, v252, 48
	v_readlane_b32 s12, v252, 56
	v_readlane_b32 s13, v252, 57
	s_mov_b32 s4, 0xf800000
	v_readlane_b32 s10, v252, 54
	v_readlane_b32 s11, v252, 55
	v_readlane_b32 s8, v252, 52
	v_readlane_b32 s9, v252, 53
	v_lshl_add_u64 v[112:113], s[10:11], 0, v[144:145]
	v_add_f32_e32 v101, v101, v103
	v_fma_f32 v101, v101, 0.5, -v99
	v_add_f32_e32 v95, v95, v97
	v_fma_f32 v95, v95, 0.5, -v91
	v_readlane_b32 s5, v252, 49
	v_readlane_b32 s6, v252, 50
	v_readlane_b32 s7, v252, 51
	v_readlane_b32 s14, v252, 58
	v_readlane_b32 s15, v252, 59
	v_readlane_b32 s16, v252, 60
	v_readlane_b32 s17, v252, 61
	v_readlane_b32 s18, v252, 62
	v_readlane_b32 s19, v252, 63
	s_waitcnt vmcnt(7)
	v_mov_b32_e32 v107, v236
	global_load_dword v244, v[78:79], off offset:256
	v_fmac_f32_e32 v109, v111, v107
	v_mov_b32_e32 v111, v1
	v_lshl_add_u64 v[110:111], v[142:143], 0, v[110:111]
	global_store_dword v[110:111], v109, off
	v_add_f32_e32 v109, v165, v171
	v_fma_f32 v109, v109, 0.5, -v168
	s_waitcnt vmcnt(8)
	v_mov_b32_e32 v107, v237
	global_load_dword v245, v[30:31], off offset:2560
	v_fmac_f32_e32 v168, v109, v107
	global_store_dword v[146:147], v168, off offset:1024
	v_add_f32_e32 v109, v170, v175
	v_fma_f32 v109, v109, 0.5, -v173
	s_waitcnt vmcnt(9)
	v_mov_b32_e32 v107, v238
	global_load_dword v246, v[78:79], off offset:512
	v_fmac_f32_e32 v173, v109, v107
	global_store_dword v[146:147], v173, off offset:1280
	v_add_f32_e32 v109, v174, v179
	v_fma_f32 v109, v109, 0.5, -v176
	s_waitcnt vmcnt(10)
	v_mov_b32_e32 v107, v239
	global_load_dword v247, v[42:43], off
	v_fmac_f32_e32 v176, v109, v107
	global_store_dword v[146:147], v176, off offset:1536
	v_add_f32_e32 v109, v178, v183
	v_fma_f32 v109, v109, 0.5, -v177
	s_waitcnt vmcnt(11)
	v_mov_b32_e32 v107, v240
	global_load_dword v248, v[80:81], off offset:-2048
	v_fmac_f32_e32 v177, v109, v107
	v_mov_b32_e32 v109, v1
	v_lshl_add_u64 v[108:109], v[142:143], 0, v[108:109]
	global_store_dword v[108:109], v177, off
	v_add_f32_e32 v108, v182, v184
	v_fma_f32 v108, v108, 0.5, -v180
	s_waitcnt vmcnt(12)
	v_mov_b32_e32 v107, v241
	global_load_dword v249, v[30:31], off offset:3072
	v_fmac_f32_e32 v180, v108, v107
	v_lshl_add_u64 v[108:109], v[136:137], 0, v[16:17]
	v_lshlrev_b64 v[108:109], 2, v[108:109]
	v_lshl_add_u64 v[110:111], s[12:13], 0, v[108:109]
	global_store_dword v[110:111], v180, off offset:-2048
	v_lshl_add_u64 v[108:109], s[8:9], 0, v[108:109]
	s_waitcnt vmcnt(13)
	v_mov_b32_e32 v107, v242
	global_load_dword v250, v[78:79], off offset:1024
	v_mul_f32_e32 v107, v180, v107
	v_mul_f32_e32 v110, v107, v107
	s_nop 1
	v_mov_b32_dpp v110, v110 quad_perm:[1,0,3,2] row_mask:0xf bank_mask:0xf bound_ctrl:1
	v_fmac_f32_e32 v110, v107, v107
	s_nop 1
	v_add_f32_dpp v110, v110, v110 quad_perm:[2,3,0,1] row_mask:0xf bank_mask:0xf bound_ctrl:1
	s_nop 1
	v_add_f32_dpp v110, v110, v110 row_half_mirror row_mask:0xf bank_mask:0xf bound_ctrl:1
	s_nop 1
	v_add_f32_dpp v110, v110, v110 row_mirror row_mask:0xf bank_mask:0xf bound_ctrl:1
	ds_bpermute_b32 v111, v87, v110
	s_waitcnt lgkmcnt(0)
	v_add_f32_e32 v110, v110, v111
	ds_bpermute_b32 v111, v89, v110
	s_waitcnt lgkmcnt(0)
	v_add_f32_e32 v110, v110, v111
	v_cmp_gt_f32_e32 vcc, s4, v110
	v_mul_f32_e32 v111, 0x4f800000, v110
	s_nop 0
	v_cndmask_b32_e32 v110, v110, v111, vcc
	v_sqrt_f32_e32 v111, v110
	s_nop 0
	v_add_u32_e32 v142, -1, v111
	v_fma_f32 v143, -v142, v111, v110
	v_cmp_ge_f32_e64 s[44:45], 0, v143
	v_add_u32_e32 v143, 1, v111
	s_nop 0
	v_cndmask_b32_e64 v142, v111, v142, s[44:45]
	v_fma_f32 v111, -v143, v111, v110
	v_cmp_lt_f32_e64 s[44:45], 0, v111
	s_nop 1
	v_cndmask_b32_e64 v111, v142, v143, s[44:45]
	v_mul_f32_e32 v142, 0x37800000, v111
	v_cndmask_b32_e32 v111, v111, v142, vcc
	v_cmp_class_f32_e32 vcc, v110, v187
	s_nop 1
	v_cndmask_b32_e32 v110, v111, v110, vcc
	v_max_f32_e32 v110, 0x2b8cbccc, v110
	v_div_scale_f32 v111, s[2:3], v110, v110, v107
	v_rcp_f32_e32 v142, v111
	s_nop 0
	v_fma_f32 v143, -v111, v142, 1.0
	v_fmac_f32_e32 v142, v143, v142
	v_div_scale_f32 v143, vcc, v107, v110, v107
	v_mul_f32_e32 v144, v143, v142
	v_fma_f32 v145, -v111, v144, v143
	v_fmac_f32_e32 v144, v145, v142
	v_fma_f32 v111, -v111, v144, v143
	v_div_fmas_f32 v111, v111, v142, v144
	v_div_fixup_f32 v107, v111, v110, v107
	global_store_dword v[108:109], v107, off offset:-2048
	v_add_f32_e32 v108, v167, v172
	v_fma_f32 v108, v108, 0.5, -v166
	s_waitcnt vmcnt(14)
	v_mov_b32_e32 v107, v243
	global_load_dword v236, v[30:31], off offset:3328
	v_fmac_f32_e32 v166, v108, v107
	v_lshl_add_u64 v[108:109], v[136:137], 0, v[18:19]
	v_lshlrev_b64 v[108:109], 2, v[108:109]
	v_lshl_add_u64 v[110:111], s[12:13], 0, v[108:109]
	global_store_dword v[110:111], v166, off offset:-2048
	v_lshl_add_u64 v[108:109], s[8:9], 0, v[108:109]
	s_waitcnt vmcnt(15)
	v_mov_b32_e32 v107, v244
	global_load_dword v237, v[78:79], off offset:1280
	v_mul_f32_e32 v107, v166, v107
	v_mul_f32_e32 v110, v107, v107
	s_nop 1
	v_mov_b32_dpp v110, v110 quad_perm:[1,0,3,2] row_mask:0xf bank_mask:0xf bound_ctrl:1
	v_fmac_f32_e32 v110, v107, v107
	s_nop 1
	v_add_f32_dpp v110, v110, v110 quad_perm:[2,3,0,1] row_mask:0xf bank_mask:0xf bound_ctrl:1
	s_nop 1
	v_add_f32_dpp v110, v110, v110 row_half_mirror row_mask:0xf bank_mask:0xf bound_ctrl:1
	s_nop 1
	v_add_f32_dpp v110, v110, v110 row_mirror row_mask:0xf bank_mask:0xf bound_ctrl:1
	ds_bpermute_b32 v111, v87, v110
	s_waitcnt lgkmcnt(0)
	v_add_f32_e32 v110, v110, v111
	ds_bpermute_b32 v111, v89, v110
	s_waitcnt lgkmcnt(0)
	v_add_f32_e32 v110, v110, v111
	v_cmp_gt_f32_e32 vcc, s4, v110
	v_mul_f32_e32 v111, 0x4f800000, v110
	s_nop 0
	v_cndmask_b32_e32 v110, v110, v111, vcc
	v_sqrt_f32_e32 v111, v110
	s_nop 0
	v_add_u32_e32 v142, -1, v111
	v_fma_f32 v143, -v142, v111, v110
	v_cmp_ge_f32_e64 s[44:45], 0, v143
	v_add_u32_e32 v143, 1, v111
	s_nop 0
	v_cndmask_b32_e64 v142, v111, v142, s[44:45]
	v_fma_f32 v111, -v143, v111, v110
	v_cmp_lt_f32_e64 s[44:45], 0, v111
	s_nop 1
	v_cndmask_b32_e64 v111, v142, v143, s[44:45]
	v_mul_f32_e32 v142, 0x37800000, v111
	v_cndmask_b32_e32 v111, v111, v142, vcc
	v_cmp_class_f32_e32 vcc, v110, v187
	s_nop 1
	v_cndmask_b32_e32 v110, v111, v110, vcc
	v_max_f32_e32 v110, 0x2b8cbccc, v110
	v_div_scale_f32 v111, s[2:3], v110, v110, v107
	v_rcp_f32_e32 v142, v111
	s_nop 0
	v_fma_f32 v143, -v111, v142, 1.0
	v_fmac_f32_e32 v142, v143, v142
	v_div_scale_f32 v143, vcc, v107, v110, v107
	v_mul_f32_e32 v144, v143, v142
	v_fma_f32 v145, -v111, v144, v143
	v_fmac_f32_e32 v144, v145, v142
	v_fma_f32 v111, -v111, v144, v143
	v_div_fmas_f32 v111, v111, v142, v144
	v_div_fixup_f32 v107, v111, v110, v107
	global_store_dword v[108:109], v107, off offset:-2048
	v_add_f32_e32 v108, v163, v164
	v_fma_f32 v108, v108, 0.5, -v162
	s_waitcnt vmcnt(15)
	v_mov_b32_e32 v107, v245
	global_load_dword v238, v[30:31], off offset:3584
	v_fmac_f32_e32 v162, v108, v107
	v_lshl_add_u64 v[108:109], v[136:137], 0, v[20:21]
	v_lshlrev_b64 v[108:109], 2, v[108:109]
	v_lshl_add_u64 v[110:111], s[12:13], 0, v[108:109]
	global_store_dword v[110:111], v162, off offset:-2048
	v_lshl_add_u64 v[108:109], s[8:9], 0, v[108:109]
	s_waitcnt vmcnt(15)
	v_mov_b32_e32 v107, v246
	global_load_dword v239, v[78:79], off offset:1536
	v_mul_f32_e32 v107, v162, v107
	v_mul_f32_e32 v110, v107, v107
	s_nop 1
	v_mov_b32_dpp v110, v110 quad_perm:[1,0,3,2] row_mask:0xf bank_mask:0xf bound_ctrl:1
	v_fmac_f32_e32 v110, v107, v107
	s_nop 1
	v_add_f32_dpp v110, v110, v110 quad_perm:[2,3,0,1] row_mask:0xf bank_mask:0xf bound_ctrl:1
	s_nop 1
	v_add_f32_dpp v110, v110, v110 row_half_mirror row_mask:0xf bank_mask:0xf bound_ctrl:1
	s_nop 1
	v_add_f32_dpp v110, v110, v110 row_mirror row_mask:0xf bank_mask:0xf bound_ctrl:1
	ds_bpermute_b32 v111, v87, v110
	s_waitcnt lgkmcnt(0)
	v_add_f32_e32 v110, v110, v111
	ds_bpermute_b32 v111, v89, v110
	s_waitcnt lgkmcnt(0)
	v_add_f32_e32 v110, v110, v111
	v_cmp_gt_f32_e32 vcc, s4, v110
	v_mul_f32_e32 v111, 0x4f800000, v110
	s_nop 0
	v_cndmask_b32_e32 v110, v110, v111, vcc
	v_sqrt_f32_e32 v111, v110
	s_nop 0
	v_add_u32_e32 v142, -1, v111
	v_fma_f32 v143, -v142, v111, v110
	v_cmp_ge_f32_e64 s[44:45], 0, v143
	v_add_u32_e32 v143, 1, v111
	s_nop 0
	v_cndmask_b32_e64 v142, v111, v142, s[44:45]
	v_fma_f32 v111, -v143, v111, v110
	v_cmp_lt_f32_e64 s[44:45], 0, v111
	s_nop 1
	v_cndmask_b32_e64 v111, v142, v143, s[44:45]
	v_mul_f32_e32 v142, 0x37800000, v111
	v_cndmask_b32_e32 v111, v111, v142, vcc
	v_cmp_class_f32_e32 vcc, v110, v187
	s_nop 1
	v_cndmask_b32_e32 v110, v111, v110, vcc
	v_max_f32_e32 v110, 0x2b8cbccc, v110
	v_div_scale_f32 v111, s[2:3], v110, v110, v107
	v_rcp_f32_e32 v142, v111
	s_nop 0
	v_fma_f32 v143, -v111, v142, 1.0
	v_fmac_f32_e32 v142, v143, v142
	v_div_scale_f32 v143, vcc, v107, v110, v107
	v_mul_f32_e32 v144, v143, v142
	v_fma_f32 v145, -v111, v144, v143
	v_fmac_f32_e32 v144, v145, v142
	v_fma_f32 v111, -v111, v144, v143
	v_div_fmas_f32 v111, v111, v142, v144
	v_div_fixup_f32 v107, v111, v110, v107
	global_store_dword v[108:109], v107, off offset:-2048
	v_add_f32_e32 v108, v160, v161
	v_fma_f32 v108, v108, 0.5, -v159
	s_waitcnt vmcnt(15)
	v_mov_b32_e32 v107, v247
	global_load_dword v240, v[44:45], off
	v_fmac_f32_e32 v159, v108, v107
	v_lshl_add_u64 v[108:109], v[136:137], 0, v[22:23]
	v_lshlrev_b64 v[108:109], 2, v[108:109]
	v_lshl_add_u64 v[110:111], s[12:13], 0, v[108:109]
	global_store_dword v[110:111], v159, off offset:-2048
	v_lshl_add_u64 v[108:109], s[8:9], 0, v[108:109]
	s_waitcnt vmcnt(15)
	v_mov_b32_e32 v107, v248
	global_load_dword v241, v[82:83], off offset:-2048
	v_mul_f32_e32 v107, v159, v107
	v_mul_f32_e32 v110, v107, v107
	s_nop 1
	v_mov_b32_dpp v110, v110 quad_perm:[1,0,3,2] row_mask:0xf bank_mask:0xf bound_ctrl:1
	v_fmac_f32_e32 v110, v107, v107
	s_nop 1
	v_add_f32_dpp v110, v110, v110 quad_perm:[2,3,0,1] row_mask:0xf bank_mask:0xf bound_ctrl:1
	s_nop 1
	v_add_f32_dpp v110, v110, v110 row_half_mirror row_mask:0xf bank_mask:0xf bound_ctrl:1
	s_nop 1
	v_add_f32_dpp v110, v110, v110 row_mirror row_mask:0xf bank_mask:0xf bound_ctrl:1
	ds_bpermute_b32 v111, v87, v110
	s_waitcnt lgkmcnt(0)
	v_add_f32_e32 v110, v110, v111
	ds_bpermute_b32 v111, v89, v110
	s_waitcnt lgkmcnt(0)
	v_add_f32_e32 v110, v110, v111
	v_cmp_gt_f32_e32 vcc, s4, v110
	v_mul_f32_e32 v111, 0x4f800000, v110
	s_nop 0
	v_cndmask_b32_e32 v110, v110, v111, vcc
	v_sqrt_f32_e32 v111, v110
	s_nop 0
	v_add_u32_e32 v142, -1, v111
	v_fma_f32 v143, -v142, v111, v110
	v_cmp_ge_f32_e64 s[44:45], 0, v143
	v_add_u32_e32 v143, 1, v111
	s_nop 0
	v_cndmask_b32_e64 v142, v111, v142, s[44:45]
	v_fma_f32 v111, -v143, v111, v110
	v_cmp_lt_f32_e64 s[44:45], 0, v111
	s_nop 1
	v_cndmask_b32_e64 v111, v142, v143, s[44:45]
	v_mul_f32_e32 v142, 0x37800000, v111
	v_cndmask_b32_e32 v111, v111, v142, vcc
	v_cmp_class_f32_e32 vcc, v110, v187
	s_nop 1
	v_cndmask_b32_e32 v110, v111, v110, vcc
	v_max_f32_e32 v110, 0x2b8cbccc, v110
	v_div_scale_f32 v111, s[2:3], v110, v110, v107
	v_rcp_f32_e32 v142, v111
	s_nop 0
	v_fma_f32 v143, -v111, v142, 1.0
	v_fmac_f32_e32 v142, v143, v142
	v_div_scale_f32 v143, vcc, v107, v110, v107
	v_mul_f32_e32 v144, v143, v142
	v_fma_f32 v145, -v111, v144, v143
	v_fmac_f32_e32 v144, v145, v142
	v_fma_f32 v111, -v111, v144, v143
	v_div_fmas_f32 v111, v111, v142, v144
	v_div_fixup_f32 v107, v111, v110, v107
	global_store_dword v[108:109], v107, off offset:-2048
	v_add_f32_e32 v108, v156, v157
	v_fma_f32 v108, v108, 0.5, -v105
	s_waitcnt vmcnt(15)
	v_mov_b32_e32 v107, v249
	global_load_dword v242, v[46:47], off
	v_fmac_f32_e32 v105, v108, v107
	v_lshl_add_u64 v[108:109], v[136:137], 0, v[24:25]
	v_lshlrev_b64 v[108:109], 2, v[108:109]
	v_lshl_add_u64 v[110:111], s[12:13], 0, v[108:109]
	global_store_dword v[110:111], v105, off offset:-2048
	v_lshl_add_u64 v[108:109], s[8:9], 0, v[108:109]
	s_waitcnt vmcnt(15)
	v_mov_b32_e32 v107, v250
	global_load_dword v243, v[48:49], off
	v_mul_f32_e32 v105, v105, v107
	v_mul_f32_e32 v107, v105, v105
	s_nop 1
	v_mov_b32_dpp v107, v107 quad_perm:[1,0,3,2] row_mask:0xf bank_mask:0xf bound_ctrl:1
	v_fmac_f32_e32 v107, v105, v105
	s_nop 1
	v_add_f32_dpp v107, v107, v107 quad_perm:[2,3,0,1] row_mask:0xf bank_mask:0xf bound_ctrl:1
	s_nop 1
	v_add_f32_dpp v107, v107, v107 row_half_mirror row_mask:0xf bank_mask:0xf bound_ctrl:1
	s_nop 1
	v_add_f32_dpp v107, v107, v107 row_mirror row_mask:0xf bank_mask:0xf bound_ctrl:1
	ds_bpermute_b32 v110, v87, v107
	s_waitcnt lgkmcnt(0)
	v_add_f32_e32 v107, v107, v110
	ds_bpermute_b32 v110, v89, v107
	s_waitcnt lgkmcnt(0)
	v_add_f32_e32 v107, v107, v110
	v_cmp_gt_f32_e32 vcc, s4, v107
	v_mul_f32_e32 v110, 0x4f800000, v107
	s_nop 0
	v_cndmask_b32_e32 v107, v107, v110, vcc
	v_sqrt_f32_e32 v110, v107
	s_nop 0
	v_add_u32_e32 v111, -1, v110
	v_fma_f32 v142, -v111, v110, v107
	v_cmp_ge_f32_e64 s[44:45], 0, v142
	v_add_u32_e32 v142, 1, v110
	s_nop 0
	v_cndmask_b32_e64 v111, v110, v111, s[44:45]
	v_fma_f32 v110, -v142, v110, v107
	v_cmp_lt_f32_e64 s[44:45], 0, v110
	s_nop 1
	v_cndmask_b32_e64 v110, v111, v142, s[44:45]
	v_mul_f32_e32 v111, 0x37800000, v110
	v_cndmask_b32_e32 v110, v110, v111, vcc
	v_cmp_class_f32_e32 vcc, v107, v187
	s_nop 1
	v_cndmask_b32_e32 v107, v110, v107, vcc
	v_max_f32_e32 v107, 0x2b8cbccc, v107
	v_div_scale_f32 v110, s[2:3], v107, v107, v105
	v_rcp_f32_e32 v111, v110
	s_nop 0
	v_fma_f32 v142, -v110, v111, 1.0
	v_fmac_f32_e32 v111, v142, v111
	v_div_scale_f32 v142, vcc, v105, v107, v105
	v_mul_f32_e32 v143, v142, v111
	v_fma_f32 v144, -v110, v143, v142
	v_fmac_f32_e32 v143, v144, v111
	v_fma_f32 v110, -v110, v143, v142
	v_div_fmas_f32 v110, v110, v111, v143
	v_div_fixup_f32 v105, v110, v107, v105
	global_store_dword v[108:109], v105, off offset:-2048
	v_lshl_add_u64 v[108:109], v[136:137], 0, v[26:27]
	v_lshlrev_b64 v[108:109], 2, v[108:109]
	v_lshl_add_u64 v[110:111], s[12:13], 0, v[108:109]
	v_lshl_add_u64 v[108:109], s[8:9], 0, v[108:109]
	s_waitcnt vmcnt(15)
	v_mov_b32_e32 v105, v236
	global_load_dword v244, v[50:51], off
	v_fmac_f32_e32 v99, v101, v105
	global_store_dword v[110:111], v99, off offset:-2048
	s_waitcnt vmcnt(15)
	v_mov_b32_e32 v101, v237
	global_load_dword v245, v[52:53], off
	v_mul_f32_e32 v99, v99, v101
	v_mul_f32_e32 v101, v99, v99
	s_nop 1
	v_mov_b32_dpp v101, v101 quad_perm:[1,0,3,2] row_mask:0xf bank_mask:0xf bound_ctrl:1
	v_fmac_f32_e32 v101, v99, v99
	s_nop 1
	v_add_f32_dpp v101, v101, v101 quad_perm:[2,3,0,1] row_mask:0xf bank_mask:0xf bound_ctrl:1
	s_nop 1
	v_add_f32_dpp v101, v101, v101 row_half_mirror row_mask:0xf bank_mask:0xf bound_ctrl:1
	s_nop 1
	v_add_f32_dpp v101, v101, v101 row_mirror row_mask:0xf bank_mask:0xf bound_ctrl:1
	ds_bpermute_b32 v103, v87, v101
	s_waitcnt lgkmcnt(0)
	v_add_f32_e32 v101, v101, v103
	ds_bpermute_b32 v103, v89, v101
	s_waitcnt lgkmcnt(0)
	v_add_f32_e32 v101, v101, v103
	v_cmp_gt_f32_e32 vcc, s4, v101
	v_mul_f32_e32 v103, 0x4f800000, v101
	s_nop 0
	v_cndmask_b32_e32 v101, v101, v103, vcc
	v_sqrt_f32_e32 v103, v101
	s_nop 0
	v_add_u32_e32 v105, -1, v103
	v_fma_f32 v107, -v105, v103, v101
	v_cmp_ge_f32_e64 s[44:45], 0, v107
	v_add_u32_e32 v107, 1, v103
	s_nop 0
	v_cndmask_b32_e64 v105, v103, v105, s[44:45]
	v_fma_f32 v103, -v107, v103, v101
	v_cmp_lt_f32_e64 s[44:45], 0, v103
	s_nop 1
	v_cndmask_b32_e64 v103, v105, v107, s[44:45]
	v_mul_f32_e32 v105, 0x37800000, v103
	v_cndmask_b32_e32 v103, v103, v105, vcc
	v_cmp_class_f32_e32 vcc, v101, v187
	s_nop 1
	v_cndmask_b32_e32 v101, v103, v101, vcc
	v_max_f32_e32 v101, 0x2b8cbccc, v101
	v_div_scale_f32 v103, s[2:3], v101, v101, v99
	v_rcp_f32_e32 v105, v103
	s_nop 0
	v_fma_f32 v107, -v103, v105, 1.0
	v_fmac_f32_e32 v105, v107, v105
	v_div_scale_f32 v107, vcc, v99, v101, v99
	v_mul_f32_e32 v110, v107, v105
	v_fma_f32 v111, -v103, v110, v107
	v_fmac_f32_e32 v110, v111, v105
	v_fma_f32 v103, -v103, v110, v107
	v_div_fmas_f32 v103, v103, v105, v110
	v_div_fixup_f32 v99, v103, v101, v99
	global_store_dword v[108:109], v99, off offset:-2048
	v_lshl_add_u64 v[108:109], v[136:137], 0, v[28:29]
	v_lshlrev_b64 v[108:109], 2, v[108:109]
	v_lshl_add_u64 v[110:111], s[12:13], 0, v[108:109]
	v_lshl_add_u64 v[108:109], s[8:9], 0, v[108:109]
	s_waitcnt vmcnt(15)
	v_mov_b32_e32 v99, v238
	global_load_dword v246, v[54:55], off
	v_fmac_f32_e32 v91, v95, v99
	global_store_dword v[110:111], v91, off offset:-2048
	s_waitcnt vmcnt(15)
	v_mov_b32_e32 v95, v239
	global_load_dword v247, v[56:57], off
	v_mul_f32_e32 v91, v91, v95
	v_mul_f32_e32 v95, v91, v91
	s_nop 1
	v_mov_b32_dpp v95, v95 quad_perm:[1,0,3,2] row_mask:0xf bank_mask:0xf bound_ctrl:1
	v_fmac_f32_e32 v95, v91, v91
	s_nop 1
	v_add_f32_dpp v95, v95, v95 quad_perm:[2,3,0,1] row_mask:0xf bank_mask:0xf bound_ctrl:1
	s_nop 1
	v_add_f32_dpp v95, v95, v95 row_half_mirror row_mask:0xf bank_mask:0xf bound_ctrl:1
	s_nop 1
	v_add_f32_dpp v95, v95, v95 row_mirror row_mask:0xf bank_mask:0xf bound_ctrl:1
	ds_bpermute_b32 v97, v87, v95
	s_waitcnt lgkmcnt(0)
	v_add_f32_e32 v95, v95, v97
	ds_bpermute_b32 v97, v89, v95
	s_waitcnt lgkmcnt(0)
	v_add_f32_e32 v95, v95, v97
	v_cmp_gt_f32_e32 vcc, s4, v95
	v_mul_f32_e32 v97, 0x4f800000, v95
	s_nop 0
	v_cndmask_b32_e32 v95, v95, v97, vcc
	v_sqrt_f32_e32 v97, v95
	s_nop 0
	v_add_u32_e32 v99, -1, v97
	v_fma_f32 v101, -v99, v97, v95
	v_cmp_ge_f32_e64 s[44:45], 0, v101
	v_add_u32_e32 v101, 1, v97
	s_nop 0
	v_cndmask_b32_e64 v99, v97, v99, s[44:45]
	v_fma_f32 v97, -v101, v97, v95
	v_cmp_lt_f32_e64 s[44:45], 0, v97
	s_nop 1
	v_cndmask_b32_e64 v97, v99, v101, s[44:45]
	v_mul_f32_e32 v99, 0x37800000, v97
	v_cndmask_b32_e32 v97, v97, v99, vcc
	v_cmp_class_f32_e32 vcc, v95, v187
	s_nop 1
	v_cndmask_b32_e32 v95, v97, v95, vcc
	v_max_f32_e32 v95, 0x2b8cbccc, v95
	v_div_scale_f32 v97, s[2:3], v95, v95, v91
	v_rcp_f32_e32 v99, v97
	s_nop 0
	v_fma_f32 v101, -v97, v99, 1.0
	v_fmac_f32_e32 v99, v101, v99
	v_div_scale_f32 v101, vcc, v91, v95, v91
	v_mul_f32_e32 v103, v101, v99
	v_fma_f32 v105, -v97, v103, v101
	v_fmac_f32_e32 v103, v105, v99
	v_fma_f32 v97, -v97, v103, v101
	v_div_fmas_f32 v97, v97, v99, v103
	v_div_fixup_f32 v91, v97, v95, v91
	global_store_dword v[108:109], v91, off offset:-2048
	v_add_f32_e32 v95, v231, v230
	v_lshl_add_u64 v[108:109], v[136:137], 0, v[32:33]
	v_fma_f32 v95, v95, 0.5, -v224
	v_lshlrev_b64 v[108:109], 2, v[108:109]
	v_lshl_add_u64 v[110:111], s[12:13], 0, v[108:109]
	v_lshl_add_u64 v[108:109], s[8:9], 0, v[108:109]
	v_mov_b32_e32 v103, v1
	v_mov_b32_e32 v105, v1
	s_waitcnt vmcnt(15)
	v_mov_b32_e32 v91, v240
	global_load_dword v248, v[58:59], off
	v_fmac_f32_e32 v224, v95, v91
	global_store_dword v[110:111], v224, off offset:-2048
	s_waitcnt vmcnt(15)
	v_mov_b32_e32 v91, v241
	global_load_dword v249, v[60:61], off
	v_mul_f32_e32 v91, v224, v91
	v_mul_f32_e32 v95, v91, v91
	s_nop 1
	v_mov_b32_dpp v95, v95 quad_perm:[1,0,3,2] row_mask:0xf bank_mask:0xf bound_ctrl:1
	v_fmac_f32_e32 v95, v91, v91
	s_nop 1
	v_add_f32_dpp v95, v95, v95 quad_perm:[2,3,0,1] row_mask:0xf bank_mask:0xf bound_ctrl:1
	s_nop 1
	v_add_f32_dpp v95, v95, v95 row_half_mirror row_mask:0xf bank_mask:0xf bound_ctrl:1
	s_nop 1
	v_add_f32_dpp v95, v95, v95 row_mirror row_mask:0xf bank_mask:0xf bound_ctrl:1
	ds_bpermute_b32 v87, v87, v95
	s_waitcnt lgkmcnt(0)
	v_add_f32_e32 v87, v95, v87
	ds_bpermute_b32 v89, v89, v87
	s_waitcnt lgkmcnt(0)
	v_add_f32_e32 v87, v87, v89
	v_cmp_gt_f32_e32 vcc, s4, v87
	v_mul_f32_e32 v89, 0x4f800000, v87
	s_nop 0
	v_cndmask_b32_e32 v87, v87, v89, vcc
	v_sqrt_f32_e32 v89, v87
	s_nop 0
	v_add_u32_e32 v95, -1, v89
	v_fma_f32 v97, -v95, v89, v87
	v_cmp_ge_f32_e64 s[44:45], 0, v97
	v_add_u32_e32 v97, 1, v89
	s_nop 0
	v_cndmask_b32_e64 v95, v89, v95, s[44:45]
	v_fma_f32 v89, -v97, v89, v87
	v_cmp_lt_f32_e64 s[44:45], 0, v89
	s_nop 1
	v_cndmask_b32_e64 v89, v95, v97, s[44:45]
	v_mul_f32_e32 v95, 0x37800000, v89
	v_cndmask_b32_e32 v89, v89, v95, vcc
	v_cmp_class_f32_e32 vcc, v87, v187
	s_nop 1
	v_cndmask_b32_e32 v87, v89, v87, vcc
	v_max_f32_e32 v87, 0x2b8cbccc, v87
	v_div_scale_f32 v89, s[2:3], v87, v87, v91
	v_rcp_f32_e32 v95, v89
	s_nop 0
	v_fma_f32 v97, -v89, v95, 1.0
	v_fmac_f32_e32 v95, v97, v95
	v_div_scale_f32 v97, vcc, v91, v87, v91
	v_mul_f32_e32 v99, v97, v95
	v_fma_f32 v101, -v89, v99, v97
	v_fmac_f32_e32 v99, v101, v95
	v_fma_f32 v89, -v89, v99, v97
	v_div_fmas_f32 v89, v89, v95, v99
	v_div_fixup_f32 v87, v89, v87, v91
	global_store_dword v[108:109], v87, off offset:-2048
	v_add_f32_e32 v89, v185, v204
	v_fma_f32 v89, v89, 0.5, -v152
	v_mov_b32_e32 v95, v1
	v_lshl_add_u64 v[108:109], v[112:113], 0, v[94:95]
	v_mov_b32_e32 v97, v1
	v_mov_b32_e32 v99, v1
	v_mov_b32_e32 v101, v1
	s_waitcnt vmcnt(15)
	v_mov_b32_e32 v87, v242
	global_load_dword v250, v[62:63], off
	v_fmac_f32_e32 v152, v89, v87
	global_store_dword v[108:109], v152, off offset:-4096
	v_add_f32_e32 v89, v206, v207
	v_fma_f32 v89, v89, 0.5, -v155
	v_lshl_add_u64 v[108:109], v[112:113], 0, v[96:97]
	s_waitcnt vmcnt(15)
	v_mov_b32_e32 v87, v243
	global_load_dword v236, v[64:65], off
	v_fmac_f32_e32 v155, v89, v87
	global_store_dword v[108:109], v155, off offset:-4096
	v_add_f32_e32 v89, v209, v211
	v_fma_f32 v89, v89, 0.5, -v205
	v_lshl_add_u64 v[108:109], v[112:113], 0, v[98:99]
	s_waitcnt vmcnt(15)
	v_mov_b32_e32 v87, v244
	global_load_dword v237, v[66:67], off
	v_fmac_f32_e32 v205, v89, v87
	global_store_dword v[108:109], v205, off offset:-4096
	v_add_f32_e32 v89, v215, v214
	v_fma_f32 v89, v89, 0.5, -v208
	v_lshl_add_u64 v[108:109], v[112:113], 0, v[0:1]
	s_waitcnt vmcnt(15)
	v_mov_b32_e32 v87, v245
	global_load_dword v238, v[68:69], off
	v_fmac_f32_e32 v208, v89, v87
	global_store_dword v[108:109], v208, off offset:-4096
	v_add_f32_e32 v87, v218, v219
	v_fma_f32 v87, v87, 0.5, -v216
	v_lshl_add_u64 v[108:109], v[112:113], 0, v[100:101]
	s_waitcnt vmcnt(15)
	v_mov_b32_e32 v0, v246
	global_load_dword v239, v[70:71], off
	v_fmac_f32_e32 v216, v87, v0
	global_store_dword v[108:109], v216, off offset:-4096
	v_add_f32_e32 v87, v223, v227
	v_fma_f32 v87, v87, 0.5, -v217
	v_lshl_add_u64 v[108:109], v[112:113], 0, v[102:103]
	s_waitcnt vmcnt(15)
	v_mov_b32_e32 v0, v247
	global_load_dword v240, v[72:73], off
	v_fmac_f32_e32 v217, v87, v0
	global_store_dword v[108:109], v217, off offset:-4096
	v_add_f32_e32 v87, v228, v229
	v_fma_f32 v87, v87, 0.5, -v221
	v_lshl_add_u64 v[108:109], v[112:113], 0, v[104:105]
	s_waitcnt vmcnt(15)
	v_mov_b32_e32 v0, v248
	v_fmac_f32_e32 v221, v87, v0
	global_store_dword v[108:109], v221, off offset:-4096
	v_add_f32_e32 v87, v232, v141
	v_fma_f32 v87, v87, 0.5, -v226
	v_mov_b32_e32 v141, v1
	v_lshl_add_u64 v[108:109], v[112:113], 0, v[140:141]
	s_waitcnt vmcnt(14)
	v_mov_b32_e32 v0, v249
	v_fmac_f32_e32 v226, v87, v0
	global_store_dword v[108:109], v226, off offset:-4096
	v_add_f32_e32 v87, v234, v235
	v_fma_f32 v87, v87, 0.5, -v233
	s_waitcnt vmcnt(13)
	v_mov_b32_e32 v0, v250
	v_fmac_f32_e32 v233, v87, v0
	v_mul_f32_e32 v0, 0xbfb8aa3b, v233
	v_exp_f32_e32 v0, v0
	s_nop 0
	v_add_f32_e32 v0, 1.0, v0
	v_div_scale_f32 v87, s[2:3], v0, v0, 1.0
	v_rcp_f32_e32 v89, v87
	s_movk_i32 s2, 0x300
	v_mad_i64_i32 v[106:107], s[2:3], v106, s2, v[84:85]
	v_fma_f32 v91, -v87, v89, 1.0
	v_fmac_f32_e32 v89, v91, v89
	v_div_scale_f32 v91, vcc, 1.0, v0, 1.0
	v_mul_f32_e32 v95, v91, v89
	v_fma_f32 v97, -v87, v95, v91
	v_fmac_f32_e32 v95, v97, v89
	v_fma_f32 v87, -v87, v95, v91
	v_div_fmas_f32 v87, v87, v89, v95
	v_div_fixup_f32 v0, v87, v0, 1.0
	v_cvt_pk_bf16_f32 v0, v0, s0
	global_store_short v[106:107], v0, off offset:512
	v_add_f32_e32 v87, v222, v225
	v_fma_f32 v87, v87, 0.5, -v220
	s_waitcnt vmcnt(12)
	v_mov_b32_e32 v0, v236
	v_fmac_f32_e32 v220, v87, v0
	v_mul_f32_e32 v0, 0xbfb8aa3b, v220
	v_exp_f32_e32 v0, v0
	s_nop 0
	v_add_f32_e32 v0, 1.0, v0
	v_div_scale_f32 v87, s[2:3], v0, v0, 1.0
	v_rcp_f32_e32 v89, v87
	s_nop 0
	v_fma_f32 v91, -v87, v89, 1.0
	v_fmac_f32_e32 v89, v91, v89
	v_div_scale_f32 v91, vcc, 1.0, v0, 1.0
	v_mul_f32_e32 v95, v91, v89
	v_fma_f32 v97, -v87, v95, v91
	v_fmac_f32_e32 v95, v97, v89
	v_fma_f32 v87, -v87, v95, v91
	v_div_fmas_f32 v87, v87, v89, v95
	v_div_fixup_f32 v0, v87, v0, 1.0
	v_cvt_pk_bf16_f32 v0, v0, s0
	global_store_short v[106:107], v0, off offset:640
	v_add_f32_e32 v87, v212, v213
	v_fma_f32 v87, v87, 0.5, -v210
	s_waitcnt vmcnt(11)
	v_mov_b32_e32 v0, v237
	v_fmac_f32_e32 v210, v87, v0
	v_add_f32_e32 v0, v210, v210
	v_mul_f32_e32 v0, 0x3fb8aa3b, v0
	v_exp_f32_e32 v0, v0
	s_nop 0
	v_add_f32_e32 v0, 1.0, v0
	v_div_scale_f32 v87, s[2:3], v0, v0, 2.0
	v_rcp_f32_e32 v89, v87
	s_nop 0
	v_fma_f32 v91, -v87, v89, 1.0
	v_fmac_f32_e32 v89, v91, v89
	v_div_scale_f32 v91, vcc, 2.0, v0, 2.0
	v_mul_f32_e32 v95, v91, v89
	v_fma_f32 v97, -v87, v95, v91
	v_fmac_f32_e32 v95, v97, v89
	v_fma_f32 v87, -v87, v95, v91
	v_div_fmas_f32 v87, v87, v89, v95
	v_div_fixup_f32 v0, v87, v0, 2.0
	v_sub_f32_e32 v0, 1.0, v0
	v_cvt_pk_bf16_f32 v0, v0, s0
	global_store_short v[106:107], v0, off
	v_add_f32_e32 v87, v154, v153
	v_fma_f32 v87, v87, 0.5, -v151
	s_waitcnt vmcnt(10)
	v_mov_b32_e32 v0, v238
	v_fmac_f32_e32 v151, v87, v0
	v_add_f32_e32 v0, v151, v151
	v_mul_f32_e32 v0, 0x3fb8aa3b, v0
	v_exp_f32_e32 v0, v0
	s_nop 0
	v_add_f32_e32 v0, 1.0, v0
	v_div_scale_f32 v87, s[2:3], v0, v0, 2.0
	v_rcp_f32_e32 v89, v87
	s_nop 0
	v_fma_f32 v91, -v87, v89, 1.0
	v_fmac_f32_e32 v89, v91, v89
	v_div_scale_f32 v91, vcc, 2.0, v0, 2.0
	v_mul_f32_e32 v95, v91, v89
	v_fma_f32 v97, -v87, v95, v91
	v_fmac_f32_e32 v95, v97, v89
	v_fma_f32 v87, -v87, v95, v91
	v_div_fmas_f32 v87, v87, v89, v95
	v_div_fixup_f32 v0, v87, v0, 2.0
	v_sub_f32_e32 v0, 1.0, v0
	v_cvt_pk_bf16_f32 v0, v0, s0
	global_store_short v[106:107], v0, off offset:128
	v_add_f32_e32 v87, v148, v150
	v_fma_f32 v87, v87, 0.5, -v139
	s_waitcnt vmcnt(9)
	v_mov_b32_e32 v0, v239
	v_fmac_f32_e32 v139, v87, v0
	v_cvt_pk_bf16_f32 v0, v139, s0
	global_store_short v[106:107], v0, off offset:256
	v_add_f32_e32 v87, v138, v149
	v_fma_f32 v87, v87, 0.5, -v93
	s_waitcnt vmcnt(8)
	v_mov_b32_e32 v0, v240
	v_fmac_f32_e32 v93, v87, v0
	v_cvt_pk_bf16_f32 v0, v93, s0
	global_store_short v[106:107], v0, off offset:384
